# gemm_out epilogue rewritten by hand: X tile (16 float4/thread) and the per-column gate prefetched right after the K-loop, single pass LDS-read/compute/float4 store with counted vmcnt; same f32 math (v
# speedup vs baseline: 1.0155x; 1.0155x over previous
.Lk_outl0_loop:
	s_barrier
	s_add_u32 m0, s35, 32768
	v_mfma_f32_16x16x32_bf16 v[94:97], v[110:113], v[140:143], v[94:97]
	ds_read_b128 v[22:25], v100 offset:32
	global_load_lds_dwordx4 v158, s[14:15] offset:0
	v_mfma_f32_16x16x32_bf16 v[90:93], v[110:113], v[144:147], v[90:93]
	ds_read_b128 v[46:49], v156 offset:32
	global_load_lds_dwordx4 v159, s[14:15] offset:1024
	v_mfma_f32_16x16x32_bf16 v[82:85], v[110:113], v[148:151], v[82:85]
	ds_read_b128 v[50:53], v156 offset:2080
	global_load_lds_dwordx4 v160, s[14:15] offset:2048
	v_mfma_f32_16x16x32_bf16 v[78:81], v[110:113], v[152:155], v[78:81]
	ds_read_b128 v[30:33], v100 offset:2080
	global_load_lds_dwordx4 v161, s[14:15] offset:3072
	s_add_u32 m0, s35, 49152
	v_mfma_f32_16x16x32_bf16 v[74:77], v[114:117], v[140:143], v[74:77]
	ds_read_b128 v[54:57], v156 offset:4128
	global_load_lds_dwordx4 v158, s[16:17] offset:0
	v_mfma_f32_16x16x32_bf16 v[70:73], v[114:117], v[144:147], v[70:73]
	ds_read_b128 v[58:61], v156 offset:6176
	global_load_lds_dwordx4 v159, s[16:17] offset:1024
	v_mfma_f32_16x16x32_bf16 v[66:69], v[114:117], v[148:151], v[66:69]
	ds_read_b128 v[38:41], v100 offset:4128
	global_load_lds_dwordx4 v160, s[16:17] offset:2048
	v_mfma_f32_16x16x32_bf16 v[62:65], v[114:117], v[152:155], v[62:65]
	ds_read_b128 v[42:45], v100 offset:6176
	global_load_lds_dwordx4 v161, s[16:17] offset:3072
	v_mfma_f32_16x16x32_bf16 v[34:37], v[118:121], v[140:143], v[34:37]
	v_mfma_f32_16x16x32_bf16 v[26:29], v[118:121], v[144:147], v[26:29]
	v_mfma_f32_16x16x32_bf16 v[18:21], v[118:121], v[148:151], v[18:21]
	v_mfma_f32_16x16x32_bf16 v[14:17], v[118:121], v[152:155], v[14:17]
	v_mfma_f32_16x16x32_bf16 v[10:13], v[136:139], v[140:143], v[10:13]
	v_mfma_f32_16x16x32_bf16 v[6:9], v[136:139], v[144:147], v[6:9]
	v_mfma_f32_16x16x32_bf16 v[2:5], v[136:139], v[148:151], v[2:5]
	v_mfma_f32_16x16x32_bf16 v[86:89], v[136:139], v[152:155], v[86:89]
	s_add_u32 s98, s98, 1
	s_and_b32 s98, s98, 15
	s_cmp_eq_u32 s98, 0
	s_cselect_b32 s99, 0x800, 0
	s_add_u32 s14, s14, 0x80
	s_addc_u32 s15, s15, 0
	s_sub_u32 s14, s14, s99
	s_subb_u32 s15, s15, 0
	s_add_u32 s16, s16, 0x80
	s_addc_u32 s17, s17, 0
	s_sub_u32 s16, s16, s99
	s_subb_u32 s17, s17, 0
	s_waitcnt lgkmcnt(0)
	v_mfma_f32_16x16x32_bf16 v[94:97], v[22:25], v[46:49], v[94:97]
	ds_read_b128 v[110:113], v109 offset:32
	v_mfma_f32_16x16x32_bf16 v[90:93], v[22:25], v[50:53], v[90:93]
	ds_read_b128 v[140:143], v157 offset:32
	v_mfma_f32_16x16x32_bf16 v[82:85], v[22:25], v[54:57], v[82:85]
	ds_read_b128 v[144:147], v157 offset:2080
	v_mfma_f32_16x16x32_bf16 v[78:81], v[22:25], v[58:61], v[78:81]
	ds_read_b128 v[114:117], v109 offset:2080
	v_mfma_f32_16x16x32_bf16 v[74:77], v[30:33], v[46:49], v[74:77]
	ds_read_b128 v[148:151], v157 offset:4128
	v_mfma_f32_16x16x32_bf16 v[70:73], v[30:33], v[50:53], v[70:73]
	ds_read_b128 v[152:155], v157 offset:6176
	v_mfma_f32_16x16x32_bf16 v[66:69], v[30:33], v[54:57], v[66:69]
	ds_read_b128 v[118:121], v109 offset:4128
	v_mfma_f32_16x16x32_bf16 v[62:65], v[30:33], v[58:61], v[62:65]
	ds_read_b128 v[136:139], v109 offset:6176
	v_mfma_f32_16x16x32_bf16 v[34:37], v[38:41], v[46:49], v[34:37]
	v_mfma_f32_16x16x32_bf16 v[26:29], v[38:41], v[50:53], v[26:29]
	v_mfma_f32_16x16x32_bf16 v[18:21], v[38:41], v[54:57], v[18:21]
	v_mfma_f32_16x16x32_bf16 v[14:17], v[38:41], v[58:61], v[14:17]
	v_mfma_f32_16x16x32_bf16 v[10:13], v[42:45], v[46:49], v[10:13]
	v_mfma_f32_16x16x32_bf16 v[6:9], v[42:45], v[50:53], v[6:9]
	v_mfma_f32_16x16x32_bf16 v[2:5], v[42:45], v[54:57], v[2:5]
	v_mfma_f32_16x16x32_bf16 v[86:89], v[42:45], v[58:61], v[86:89]
	s_waitcnt lgkmcnt(0)
	s_waitcnt vmcnt(0)
	s_barrier
	s_add_u32 m0, s35, 0
	v_mfma_f32_16x16x32_bf16 v[94:97], v[110:113], v[140:143], v[94:97]
	ds_read_b128 v[22:25], v100 offset:32800
	global_load_lds_dwordx4 v158, s[14:15] offset:0
	v_mfma_f32_16x16x32_bf16 v[90:93], v[110:113], v[144:147], v[90:93]
	ds_read_b128 v[46:49], v156 offset:32800
	global_load_lds_dwordx4 v159, s[14:15] offset:1024
	v_mfma_f32_16x16x32_bf16 v[82:85], v[110:113], v[148:151], v[82:85]
	ds_read_b128 v[50:53], v156 offset:34848
	global_load_lds_dwordx4 v160, s[14:15] offset:2048
	v_mfma_f32_16x16x32_bf16 v[78:81], v[110:113], v[152:155], v[78:81]
	ds_read_b128 v[30:33], v100 offset:34848
	global_load_lds_dwordx4 v161, s[14:15] offset:3072
	s_add_u32 m0, s35, 16384
	v_mfma_f32_16x16x32_bf16 v[74:77], v[114:117], v[140:143], v[74:77]
	ds_read_b128 v[54:57], v156 offset:36896
	global_load_lds_dwordx4 v158, s[16:17] offset:0
	v_mfma_f32_16x16x32_bf16 v[70:73], v[114:117], v[144:147], v[70:73]
	ds_read_b128 v[58:61], v156 offset:38944
	global_load_lds_dwordx4 v159, s[16:17] offset:1024
	v_mfma_f32_16x16x32_bf16 v[66:69], v[114:117], v[148:151], v[66:69]
	ds_read_b128 v[38:41], v100 offset:36896
	global_load_lds_dwordx4 v160, s[16:17] offset:2048
	v_mfma_f32_16x16x32_bf16 v[62:65], v[114:117], v[152:155], v[62:65]
	ds_read_b128 v[42:45], v100 offset:38944
	global_load_lds_dwordx4 v161, s[16:17] offset:3072
	v_mfma_f32_16x16x32_bf16 v[34:37], v[118:121], v[140:143], v[34:37]
	v_mfma_f32_16x16x32_bf16 v[26:29], v[118:121], v[144:147], v[26:29]
	v_mfma_f32_16x16x32_bf16 v[18:21], v[118:121], v[148:151], v[18:21]
	v_mfma_f32_16x16x32_bf16 v[14:17], v[118:121], v[152:155], v[14:17]
	v_mfma_f32_16x16x32_bf16 v[10:13], v[136:139], v[140:143], v[10:13]
	v_mfma_f32_16x16x32_bf16 v[6:9], v[136:139], v[144:147], v[6:9]
	v_mfma_f32_16x16x32_bf16 v[2:5], v[136:139], v[148:151], v[2:5]
	v_mfma_f32_16x16x32_bf16 v[86:89], v[136:139], v[152:155], v[86:89]
	s_add_u32 s98, s98, 1
	s_and_b32 s98, s98, 15
	s_cmp_eq_u32 s98, 0
	s_cselect_b32 s99, 0x800, 0
	s_add_u32 s14, s14, 0x80
	s_addc_u32 s15, s15, 0
	s_sub_u32 s14, s14, s99
	s_subb_u32 s15, s15, 0
	s_add_u32 s16, s16, 0x80
	s_addc_u32 s17, s17, 0
	s_sub_u32 s16, s16, s99
	s_subb_u32 s17, s17, 0
	s_waitcnt lgkmcnt(0)
	v_mfma_f32_16x16x32_bf16 v[94:97], v[22:25], v[46:49], v[94:97]
	ds_read_b128 v[110:113], v109 offset:32800
	v_mfma_f32_16x16x32_bf16 v[90:93], v[22:25], v[50:53], v[90:93]
	ds_read_b128 v[140:143], v157 offset:32800
	v_mfma_f32_16x16x32_bf16 v[82:85], v[22:25], v[54:57], v[82:85]
	ds_read_b128 v[144:147], v157 offset:34848
	v_mfma_f32_16x16x32_bf16 v[78:81], v[22:25], v[58:61], v[78:81]
	ds_read_b128 v[114:117], v109 offset:34848
	v_mfma_f32_16x16x32_bf16 v[74:77], v[30:33], v[46:49], v[74:77]
	ds_read_b128 v[148:151], v157 offset:36896
	v_mfma_f32_16x16x32_bf16 v[70:73], v[30:33], v[50:53], v[70:73]
	ds_read_b128 v[152:155], v157 offset:38944
	v_mfma_f32_16x16x32_bf16 v[66:69], v[30:33], v[54:57], v[66:69]
	ds_read_b128 v[118:121], v109 offset:36896
	v_mfma_f32_16x16x32_bf16 v[62:65], v[30:33], v[58:61], v[62:65]
	ds_read_b128 v[136:139], v109 offset:38944
	v_mfma_f32_16x16x32_bf16 v[34:37], v[38:41], v[46:49], v[34:37]
	v_mfma_f32_16x16x32_bf16 v[26:29], v[38:41], v[50:53], v[26:29]
	v_mfma_f32_16x16x32_bf16 v[18:21], v[38:41], v[54:57], v[18:21]
	v_mfma_f32_16x16x32_bf16 v[14:17], v[38:41], v[58:61], v[14:17]
	v_mfma_f32_16x16x32_bf16 v[10:13], v[42:45], v[46:49], v[10:13]
	v_mfma_f32_16x16x32_bf16 v[6:9], v[42:45], v[50:53], v[6:9]
	v_mfma_f32_16x16x32_bf16 v[2:5], v[42:45], v[54:57], v[2:5]
	v_mfma_f32_16x16x32_bf16 v[86:89], v[42:45], v[58:61], v[86:89]
	s_waitcnt lgkmcnt(0)
	s_waitcnt vmcnt(0)
	s_add_u32 s34, s34, 1
	s_cmp_lt_u32 s34, 7
	s_cbranch_scc1 .Lk_outl0_loop
	s_barrier
	s_add_u32 m0, s35, 32768
	v_mfma_f32_16x16x32_bf16 v[94:97], v[110:113], v[140:143], v[94:97]
	ds_read_b128 v[22:25], v100 offset:32
	global_load_lds_dwordx4 v158, s[14:15] offset:0
	v_mfma_f32_16x16x32_bf16 v[90:93], v[110:113], v[144:147], v[90:93]
	ds_read_b128 v[46:49], v156 offset:32
	global_load_lds_dwordx4 v159, s[14:15] offset:1024
	v_mfma_f32_16x16x32_bf16 v[82:85], v[110:113], v[148:151], v[82:85]
	ds_read_b128 v[50:53], v156 offset:2080
	global_load_lds_dwordx4 v160, s[14:15] offset:2048
	v_mfma_f32_16x16x32_bf16 v[78:81], v[110:113], v[152:155], v[78:81]
	ds_read_b128 v[30:33], v100 offset:2080
	global_load_lds_dwordx4 v161, s[14:15] offset:3072
	s_add_u32 m0, s35, 49152
	v_mfma_f32_16x16x32_bf16 v[74:77], v[114:117], v[140:143], v[74:77]
	ds_read_b128 v[54:57], v156 offset:4128
	global_load_lds_dwordx4 v158, s[16:17] offset:0
	v_mfma_f32_16x16x32_bf16 v[70:73], v[114:117], v[144:147], v[70:73]
	ds_read_b128 v[58:61], v156 offset:6176
	global_load_lds_dwordx4 v159, s[16:17] offset:1024
	v_mfma_f32_16x16x32_bf16 v[66:69], v[114:117], v[148:151], v[66:69]
	ds_read_b128 v[38:41], v100 offset:4128
	global_load_lds_dwordx4 v160, s[16:17] offset:2048
	v_mfma_f32_16x16x32_bf16 v[62:65], v[114:117], v[152:155], v[62:65]
	ds_read_b128 v[42:45], v100 offset:6176
	global_load_lds_dwordx4 v161, s[16:17] offset:3072
	v_mfma_f32_16x16x32_bf16 v[34:37], v[118:121], v[140:143], v[34:37]
	v_mfma_f32_16x16x32_bf16 v[26:29], v[118:121], v[144:147], v[26:29]
	v_mfma_f32_16x16x32_bf16 v[18:21], v[118:121], v[148:151], v[18:21]
	v_mfma_f32_16x16x32_bf16 v[14:17], v[118:121], v[152:155], v[14:17]
	v_mfma_f32_16x16x32_bf16 v[10:13], v[136:139], v[140:143], v[10:13]
	v_mfma_f32_16x16x32_bf16 v[6:9], v[136:139], v[144:147], v[6:9]
	v_mfma_f32_16x16x32_bf16 v[2:5], v[136:139], v[148:151], v[2:5]
	v_mfma_f32_16x16x32_bf16 v[86:89], v[136:139], v[152:155], v[86:89]
	s_add_u32 s98, s98, 1
	s_and_b32 s98, s98, 15
	s_cmp_eq_u32 s98, 0
	s_cselect_b32 s99, 0x800, 0
	s_add_u32 s14, s14, 0x80
	s_addc_u32 s15, s15, 0
	s_sub_u32 s14, s14, s99
	s_subb_u32 s15, s15, 0
	s_add_u32 s16, s16, 0x80
	s_addc_u32 s17, s17, 0
	s_sub_u32 s16, s16, s99
	s_subb_u32 s17, s17, 0
	s_waitcnt lgkmcnt(0)
	v_mfma_f32_16x16x32_bf16 v[94:97], v[22:25], v[46:49], v[94:97]
	ds_read_b128 v[110:113], v109 offset:32
	v_mfma_f32_16x16x32_bf16 v[90:93], v[22:25], v[50:53], v[90:93]
	ds_read_b128 v[140:143], v157 offset:32
	v_mfma_f32_16x16x32_bf16 v[82:85], v[22:25], v[54:57], v[82:85]
	ds_read_b128 v[144:147], v157 offset:2080
	v_mfma_f32_16x16x32_bf16 v[78:81], v[22:25], v[58:61], v[78:81]
	ds_read_b128 v[114:117], v109 offset:2080
	v_mfma_f32_16x16x32_bf16 v[74:77], v[30:33], v[46:49], v[74:77]
	ds_read_b128 v[148:151], v157 offset:4128
	v_mfma_f32_16x16x32_bf16 v[70:73], v[30:33], v[50:53], v[70:73]
	ds_read_b128 v[152:155], v157 offset:6176
	v_mfma_f32_16x16x32_bf16 v[66:69], v[30:33], v[54:57], v[66:69]
	ds_read_b128 v[118:121], v109 offset:4128
	v_mfma_f32_16x16x32_bf16 v[62:65], v[30:33], v[58:61], v[62:65]
	ds_read_b128 v[136:139], v109 offset:6176
	v_mfma_f32_16x16x32_bf16 v[34:37], v[38:41], v[46:49], v[34:37]
	v_mfma_f32_16x16x32_bf16 v[26:29], v[38:41], v[50:53], v[26:29]
	v_mfma_f32_16x16x32_bf16 v[18:21], v[38:41], v[54:57], v[18:21]
	v_mfma_f32_16x16x32_bf16 v[14:17], v[38:41], v[58:61], v[14:17]
	v_mfma_f32_16x16x32_bf16 v[10:13], v[42:45], v[46:49], v[10:13]
	v_mfma_f32_16x16x32_bf16 v[6:9], v[42:45], v[50:53], v[6:9]
	v_mfma_f32_16x16x32_bf16 v[2:5], v[42:45], v[54:57], v[2:5]
	v_mfma_f32_16x16x32_bf16 v[86:89], v[42:45], v[58:61], v[86:89]
	s_waitcnt lgkmcnt(0)
	s_waitcnt vmcnt(0)
	s_barrier
	v_mfma_f32_16x16x32_bf16 v[94:97], v[110:113], v[140:143], v[94:97]
	ds_read_b128 v[22:25], v100 offset:32800
	v_mfma_f32_16x16x32_bf16 v[90:93], v[110:113], v[144:147], v[90:93]
	ds_read_b128 v[46:49], v156 offset:32800
	v_mfma_f32_16x16x32_bf16 v[82:85], v[110:113], v[148:151], v[82:85]
	ds_read_b128 v[50:53], v156 offset:34848
	v_mfma_f32_16x16x32_bf16 v[78:81], v[110:113], v[152:155], v[78:81]
	ds_read_b128 v[30:33], v100 offset:34848
	v_mfma_f32_16x16x32_bf16 v[74:77], v[114:117], v[140:143], v[74:77]
	ds_read_b128 v[54:57], v156 offset:36896
	v_mfma_f32_16x16x32_bf16 v[70:73], v[114:117], v[144:147], v[70:73]
	ds_read_b128 v[58:61], v156 offset:38944
	v_mfma_f32_16x16x32_bf16 v[66:69], v[114:117], v[148:151], v[66:69]
	ds_read_b128 v[38:41], v100 offset:36896
	v_mfma_f32_16x16x32_bf16 v[62:65], v[114:117], v[152:155], v[62:65]
	ds_read_b128 v[42:45], v100 offset:38944
	v_mfma_f32_16x16x32_bf16 v[34:37], v[118:121], v[140:143], v[34:37]
	v_mfma_f32_16x16x32_bf16 v[26:29], v[118:121], v[144:147], v[26:29]
	v_mfma_f32_16x16x32_bf16 v[18:21], v[118:121], v[148:151], v[18:21]
	v_mfma_f32_16x16x32_bf16 v[14:17], v[118:121], v[152:155], v[14:17]
	v_mfma_f32_16x16x32_bf16 v[10:13], v[136:139], v[140:143], v[10:13]
	v_mfma_f32_16x16x32_bf16 v[6:9], v[136:139], v[144:147], v[6:9]
	v_mfma_f32_16x16x32_bf16 v[2:5], v[136:139], v[148:151], v[2:5]
	v_mfma_f32_16x16x32_bf16 v[86:89], v[136:139], v[152:155], v[86:89]
	s_waitcnt lgkmcnt(0)
	v_mfma_f32_16x16x32_bf16 v[94:97], v[22:25], v[46:49], v[94:97]
	ds_read_b128 v[110:113], v109 offset:32800
	v_mfma_f32_16x16x32_bf16 v[90:93], v[22:25], v[50:53], v[90:93]
	ds_read_b128 v[140:143], v157 offset:32800
	v_mfma_f32_16x16x32_bf16 v[82:85], v[22:25], v[54:57], v[82:85]
	ds_read_b128 v[144:147], v157 offset:34848
	v_mfma_f32_16x16x32_bf16 v[78:81], v[22:25], v[58:61], v[78:81]
	ds_read_b128 v[114:117], v109 offset:34848
	v_mfma_f32_16x16x32_bf16 v[74:77], v[30:33], v[46:49], v[74:77]
	ds_read_b128 v[148:151], v157 offset:36896
	v_mfma_f32_16x16x32_bf16 v[70:73], v[30:33], v[50:53], v[70:73]
	ds_read_b128 v[152:155], v157 offset:38944
	v_mfma_f32_16x16x32_bf16 v[66:69], v[30:33], v[54:57], v[66:69]
	ds_read_b128 v[118:121], v109 offset:36896
	v_mfma_f32_16x16x32_bf16 v[62:65], v[30:33], v[58:61], v[62:65]
	ds_read_b128 v[136:139], v109 offset:38944
	v_mfma_f32_16x16x32_bf16 v[34:37], v[38:41], v[46:49], v[34:37]
	v_mfma_f32_16x16x32_bf16 v[26:29], v[38:41], v[50:53], v[26:29]
	v_mfma_f32_16x16x32_bf16 v[18:21], v[38:41], v[54:57], v[18:21]
	v_mfma_f32_16x16x32_bf16 v[14:17], v[38:41], v[58:61], v[14:17]
	v_mfma_f32_16x16x32_bf16 v[10:13], v[42:45], v[46:49], v[10:13]
	v_mfma_f32_16x16x32_bf16 v[6:9], v[42:45], v[50:53], v[6:9]
	v_mfma_f32_16x16x32_bf16 v[2:5], v[42:45], v[54:57], v[2:5]
	v_mfma_f32_16x16x32_bf16 v[86:89], v[42:45], v[58:61], v[86:89]
	s_waitcnt lgkmcnt(0)
	v_mfma_f32_16x16x32_bf16 v[94:97], v[110:113], v[140:143], v[94:97]
	v_mfma_f32_16x16x32_bf16 v[90:93], v[110:113], v[144:147], v[90:93]
	v_mfma_f32_16x16x32_bf16 v[82:85], v[110:113], v[148:151], v[82:85]
	v_mfma_f32_16x16x32_bf16 v[78:81], v[110:113], v[152:155], v[78:81]
	v_mfma_f32_16x16x32_bf16 v[74:77], v[114:117], v[140:143], v[74:77]
	v_mfma_f32_16x16x32_bf16 v[70:73], v[114:117], v[144:147], v[70:73]
	v_mfma_f32_16x16x32_bf16 v[66:69], v[114:117], v[148:151], v[66:69]
	v_mfma_f32_16x16x32_bf16 v[62:65], v[114:117], v[152:155], v[62:65]
	v_mfma_f32_16x16x32_bf16 v[34:37], v[118:121], v[140:143], v[34:37]
	v_mfma_f32_16x16x32_bf16 v[26:29], v[118:121], v[144:147], v[26:29]
	v_mfma_f32_16x16x32_bf16 v[18:21], v[118:121], v[148:151], v[18:21]
	v_mfma_f32_16x16x32_bf16 v[14:17], v[118:121], v[152:155], v[14:17]
	v_mfma_f32_16x16x32_bf16 v[10:13], v[136:139], v[140:143], v[10:13]
	v_mfma_f32_16x16x32_bf16 v[6:9], v[136:139], v[144:147], v[6:9]
	v_mfma_f32_16x16x32_bf16 v[2:5], v[136:139], v[148:151], v[2:5]
	v_mfma_f32_16x16x32_bf16 v[86:89], v[136:139], v[152:155], v[86:89]
	s_mul_i32 s14, s33, 12
	s_sub_u32 s14, s31, s14
	v_readlane_b32 s15, v255, 16
	s_and_b32 s15, s15, 7
	s_lshl_b32 s14, s14, 3
	s_or_b32 s14, s14, s15
	s_lshl_b32 s100, s14, 7
	s_lshl_b32 s101, s33, 9
	v_lshrrev_b32_e32 v114, 5, v0
	v_and_b32_e32 v114, 7, v114
	v_and_b32_e32 v115, 31, v0
	v_lshlrev_b32_e32 v115, 4, v115
	v_lshl_or_b32 v114, v114, 12, v115
	s_sub_u32 s14, s100, 0x2000
	s_lshr_b32 s14, s14, 10
	s_add_u32 s14, s14, 1
	s_cmp_lt_u32 s100, 0x2000
	s_cselect_b32 s14, 0, s14
	s_mul_i32 s14, s14, 0x6000
	s_add_u32 s14, s14, s101
	s_add_u32 s16, s42, s14
	s_addc_u32 s17, s43, 0
	s_add_u32 s16, s16, 0x6ea6000
	s_addc_u32 s17, s17, 0
	global_load_dwordx4 v[110:113], v115, s[16:17]
	s_lshl_b32 s14, s100, 12
	s_add_u32 s14, s14, s101
	s_add_u32 s16, s42, s14
	s_addc_u32 s17, s43, 0
	s_add_u32 s16, s16, 0x6f24000
	s_addc_u32 s17, s17, 0
	global_load_dwordx4 v[136:139], v114, s[16:17] nt
	s_add_u32 s16, s16, 0x8000
	s_addc_u32 s17, s17, 0
	global_load_dwordx4 v[140:143], v114, s[16:17] nt
	s_add_u32 s16, s16, 0x8000
	s_addc_u32 s17, s17, 0
	global_load_dwordx4 v[144:147], v114, s[16:17] nt
	s_add_u32 s16, s16, 0x8000
	s_addc_u32 s17, s17, 0
	global_load_dwordx4 v[148:151], v114, s[16:17] nt
	s_add_u32 s16, s16, 0x8000
	s_addc_u32 s17, s17, 0
	global_load_dwordx4 v[152:155], v114, s[16:17] nt
	s_add_u32 s16, s16, 0x8000
	s_addc_u32 s17, s17, 0
	global_load_dwordx4 v[156:159], v114, s[16:17] nt
	s_add_u32 s16, s16, 0x8000
	s_addc_u32 s17, s17, 0
	global_load_dwordx4 v[160:163], v114, s[16:17] nt
	s_add_u32 s16, s16, 0x8000
	s_addc_u32 s17, s17, 0
	global_load_dwordx4 v[164:167], v114, s[16:17] nt
	s_add_u32 s16, s16, 0x8000
	s_addc_u32 s17, s17, 0
	global_load_dwordx4 v[168:171], v114, s[16:17] nt
	s_add_u32 s16, s16, 0x8000
	s_addc_u32 s17, s17, 0
	global_load_dwordx4 v[172:175], v114, s[16:17] nt
	s_add_u32 s16, s16, 0x8000
	s_addc_u32 s17, s17, 0
	global_load_dwordx4 v[188:191], v114, s[16:17] nt
	s_add_u32 s16, s16, 0x8000
	s_addc_u32 s17, s17, 0
	global_load_dwordx4 v[192:195], v114, s[16:17] nt
	s_add_u32 s16, s16, 0x8000
	s_addc_u32 s17, s17, 0
	global_load_dwordx4 v[196:199], v114, s[16:17] nt
	s_add_u32 s16, s16, 0x8000
	s_addc_u32 s17, s17, 0
	global_load_dwordx4 v[200:203], v114, s[16:17] nt
	s_add_u32 s16, s16, 0x8000
	s_addc_u32 s17, s17, 0
	global_load_dwordx4 v[204:207], v114, s[16:17] nt
	s_add_u32 s16, s16, 0x8000
	s_addc_u32 s17, s17, 0
	global_load_dwordx4 v[208:211], v114, s[16:17] nt
	v_add_u32_e32 v22, 0x400, v123
	s_barrier
	ds_write2_b32 v123, v94, v90 offset1:16
	ds_write2_b32 v123, v95, v91 offset0:132 offset1:148
	ds_write2_b32 v22, v96, v92 offset0:8 offset1:24
	ds_write2_b32 v22, v97, v93 offset0:140 offset1:156
	ds_write2_b32 v123, v82, v78 offset0:32 offset1:48
	ds_write2_b32 v123, v83, v79 offset0:164 offset1:180
	ds_write2_b32 v22, v84, v80 offset0:40 offset1:56
	ds_write2_b32 v22, v85, v81 offset0:172 offset1:188
	v_add_u32_e32 v22, 0x2000, v123
	v_add_u32_e32 v23, 0x2400, v123
	ds_write2_b32 v22, v74, v70 offset0:64 offset1:80
	ds_write2_b32 v22, v75, v71 offset0:196 offset1:212
	ds_write2_b32 v23, v76, v72 offset0:72 offset1:88
	ds_write2_b32 v23, v77, v73 offset0:204 offset1:220
	ds_write2_b32 v22, v66, v62 offset0:96 offset1:112
	ds_write2_b32 v22, v67, v63 offset0:228 offset1:244
	ds_write2_b32 v23, v68, v64 offset0:104 offset1:120
	ds_write2_b32 v23, v69, v65 offset0:236 offset1:252
	v_add_u32_e32 v22, 0x4000, v123
	v_add_u32_e32 v23, 0x4400, v123
	v_add_u32_e32 v24, 0x4800, v123
	ds_write2_b32 v22, v34, v26 offset0:128 offset1:144
	ds_write2_b32 v23, v35, v27 offset0:4 offset1:20
	ds_write2_b32 v23, v36, v28 offset0:136 offset1:152
	ds_write2_b32 v24, v37, v29 offset0:12 offset1:28
	ds_write2_b32 v22, v18, v14 offset0:160 offset1:176
	ds_write2_b32 v23, v19, v15 offset0:36 offset1:52
	ds_write2_b32 v23, v20, v16 offset0:168 offset1:184
	ds_write2_b32 v24, v21, v17 offset0:44 offset1:60
	v_add_u32_e32 v14, 0x6000, v123
	ds_write2_b32 v14, v10, v6 offset0:192 offset1:208
	v_add_u32_e32 v6, 0x6400, v123
	ds_write2_b32 v6, v11, v7 offset0:68 offset1:84
	ds_write2_b32 v6, v12, v8 offset0:200 offset1:216
	v_add_u32_e32 v7, 0x6800, v123
	s_lshl_b32 s4, s33, 9
	ds_write2_b32 v7, v13, v9 offset0:76 offset1:92
	ds_write2_b32 v14, v2, v86 offset0:224 offset1:240
	ds_write2_b32 v6, v3, v87 offset0:100 offset1:116
	ds_write2_b32 v6, v4, v88 offset0:232 offset1:248
	ds_write2_b32 v7, v5, v89 offset0:108 offset1:124
	v_lshl_add_u64 v[2:3], v[102:103], 0, s[4:5]
	v_lshl_add_u64 v[4:5], v[104:105], 0, s[4:5]
	s_lshl_b32 s4, s31, 10
	s_mul_hi_u32 s14, s31, 0x15555556
	s_lshl_b32 s15, s33, 7
	v_or_b32_e32 v6, s4, v125
	s_mulk_i32 s14, 0x3000
	v_or_b32_e32 v7, s4, v127
	v_or_b32_e32 v8, s4, v129
	v_or_b32_e32 v9, s4, v133
	v_subrev_u32_e32 v6, s14, v6
	v_subrev_u32_e32 v7, s14, v7
	v_subrev_u32_e32 v8, s14, v8
	v_subrev_u32_e32 v9, s14, v9
	s_mov_b32 s14, 0
	s_lshl_b32 s4, s15, 2
	v_mov_b32_e32 v10, v132
	v_mov_b32_e32 v11, v128
	v_mov_b32_e32 v12, v126
	v_mov_b32_e32 v13, v124
	s_waitcnt lgkmcnt(0)
	s_barrier
	s_mov_b32 s98, 0x3fb504f3
	v_lshrrev_b32_e32 v116, 5, v0
	v_and_b32_e32 v116, 7, v116
	v_mul_u32_u24_e32 v116, 0x210, v116
	v_and_b32_e32 v38, 31, v0
	v_lshl_add_u32 v116, v38, 4, v116
	s_lshl_b32 s14, s100, 12
	s_add_u32 s14, s14, s101
	s_add_u32 s16, s42, s14
	s_addc_u32 s17, s43, 0
	s_add_u32 s16, s16, 0xfb24000
	s_addc_u32 s17, s17, 0
	ds_read_b128 v[38:41], v116 offset:32
	ds_read_b128 v[42:45], v116 offset:4256
	ds_read_b128 v[46:49], v116 offset:8480
	ds_read_b128 v[50:53], v116 offset:12704
	s_waitcnt vmcnt(15) lgkmcnt(3)
	v_pk_mul_f32 v[38:39], v[38:39], v[110:111]
	v_pk_mul_f32 v[40:41], v[40:41], v[112:113]
	v_pk_fma_f32 v[136:137], v[136:137], s[98:99], v[38:39] op_sel_hi:[1,0,1]
	v_pk_fma_f32 v[138:139], v[138:139], s[98:99], v[40:41] op_sel_hi:[1,0,1]
	ds_read_b128 v[38:41], v116 offset:16928
	global_store_dwordx4 v114, v[136:139], s[16:17]
	s_add_u32 s16, s16, 0x8000
	s_addc_u32 s17, s17, 0
	s_waitcnt vmcnt(15) lgkmcnt(3)
	v_pk_mul_f32 v[42:43], v[42:43], v[110:111]
	v_pk_mul_f32 v[44:45], v[44:45], v[112:113]
	v_pk_fma_f32 v[140:141], v[140:141], s[98:99], v[42:43] op_sel_hi:[1,0,1]
	v_pk_fma_f32 v[142:143], v[142:143], s[98:99], v[44:45] op_sel_hi:[1,0,1]
	ds_read_b128 v[42:45], v116 offset:21152
	global_store_dwordx4 v114, v[140:143], s[16:17]
	s_add_u32 s16, s16, 0x8000
	s_addc_u32 s17, s17, 0
	s_waitcnt vmcnt(15) lgkmcnt(3)
	v_pk_mul_f32 v[46:47], v[46:47], v[110:111]
	v_pk_mul_f32 v[48:49], v[48:49], v[112:113]
	v_pk_fma_f32 v[144:145], v[144:145], s[98:99], v[46:47] op_sel_hi:[1,0,1]
	v_pk_fma_f32 v[146:147], v[146:147], s[98:99], v[48:49] op_sel_hi:[1,0,1]
	ds_read_b128 v[46:49], v116 offset:25376
	global_store_dwordx4 v114, v[144:147], s[16:17]
	s_add_u32 s16, s16, 0x8000
	s_addc_u32 s17, s17, 0
	s_waitcnt vmcnt(15) lgkmcnt(3)
	v_pk_mul_f32 v[50:51], v[50:51], v[110:111]
	v_pk_mul_f32 v[52:53], v[52:53], v[112:113]
	v_pk_fma_f32 v[148:149], v[148:149], s[98:99], v[50:51] op_sel_hi:[1,0,1]
	v_pk_fma_f32 v[150:151], v[150:151], s[98:99], v[52:53] op_sel_hi:[1,0,1]
	ds_read_b128 v[50:53], v116 offset:29600
	global_store_dwordx4 v114, v[148:151], s[16:17]
	s_add_u32 s16, s16, 0x8000
	s_addc_u32 s17, s17, 0
	s_waitcnt vmcnt(15) lgkmcnt(3)
	v_pk_mul_f32 v[38:39], v[38:39], v[110:111]
	v_pk_mul_f32 v[40:41], v[40:41], v[112:113]
	v_pk_fma_f32 v[152:153], v[152:153], s[98:99], v[38:39] op_sel_hi:[1,0,1]
	v_pk_fma_f32 v[154:155], v[154:155], s[98:99], v[40:41] op_sel_hi:[1,0,1]
	ds_read_b128 v[38:41], v116 offset:33824
	global_store_dwordx4 v114, v[152:155], s[16:17]
	s_add_u32 s16, s16, 0x8000
	s_addc_u32 s17, s17, 0
	s_waitcnt vmcnt(15) lgkmcnt(3)
	v_pk_mul_f32 v[42:43], v[42:43], v[110:111]
	v_pk_mul_f32 v[44:45], v[44:45], v[112:113]
	v_pk_fma_f32 v[156:157], v[156:157], s[98:99], v[42:43] op_sel_hi:[1,0,1]
	v_pk_fma_f32 v[158:159], v[158:159], s[98:99], v[44:45] op_sel_hi:[1,0,1]
	ds_read_b128 v[42:45], v116 offset:38048
	global_store_dwordx4 v114, v[156:159], s[16:17]
	s_add_u32 s16, s16, 0x8000
	s_addc_u32 s17, s17, 0
	s_waitcnt vmcnt(15) lgkmcnt(3)
	v_pk_mul_f32 v[46:47], v[46:47], v[110:111]
	v_pk_mul_f32 v[48:49], v[48:49], v[112:113]
	v_pk_fma_f32 v[160:161], v[160:161], s[98:99], v[46:47] op_sel_hi:[1,0,1]
	v_pk_fma_f32 v[162:163], v[162:163], s[98:99], v[48:49] op_sel_hi:[1,0,1]
	ds_read_b128 v[46:49], v116 offset:42272
	global_store_dwordx4 v114, v[160:163], s[16:17]
	s_add_u32 s16, s16, 0x8000
	s_addc_u32 s17, s17, 0
	s_waitcnt vmcnt(15) lgkmcnt(3)
	v_pk_mul_f32 v[50:51], v[50:51], v[110:111]
	v_pk_mul_f32 v[52:53], v[52:53], v[112:113]
	v_pk_fma_f32 v[164:165], v[164:165], s[98:99], v[50:51] op_sel_hi:[1,0,1]
	v_pk_fma_f32 v[166:167], v[166:167], s[98:99], v[52:53] op_sel_hi:[1,0,1]
	ds_read_b128 v[50:53], v116 offset:46496
	global_store_dwordx4 v114, v[164:167], s[16:17]
	s_add_u32 s16, s16, 0x8000
	s_addc_u32 s17, s17, 0
	s_waitcnt vmcnt(15) lgkmcnt(3)
	v_pk_mul_f32 v[38:39], v[38:39], v[110:111]
	v_pk_mul_f32 v[40:41], v[40:41], v[112:113]
	v_pk_fma_f32 v[168:169], v[168:169], s[98:99], v[38:39] op_sel_hi:[1,0,1]
	v_pk_fma_f32 v[170:171], v[170:171], s[98:99], v[40:41] op_sel_hi:[1,0,1]
	ds_read_b128 v[38:41], v116 offset:50720
	global_store_dwordx4 v114, v[168:171], s[16:17]
	s_add_u32 s16, s16, 0x8000
	s_addc_u32 s17, s17, 0
	s_waitcnt vmcnt(15) lgkmcnt(3)
	v_pk_mul_f32 v[42:43], v[42:43], v[110:111]
	v_pk_mul_f32 v[44:45], v[44:45], v[112:113]
	v_pk_fma_f32 v[172:173], v[172:173], s[98:99], v[42:43] op_sel_hi:[1,0,1]
	v_pk_fma_f32 v[174:175], v[174:175], s[98:99], v[44:45] op_sel_hi:[1,0,1]
	ds_read_b128 v[42:45], v116 offset:54944
	global_store_dwordx4 v114, v[172:175], s[16:17]
	s_add_u32 s16, s16, 0x8000
	s_addc_u32 s17, s17, 0
	s_waitcnt vmcnt(15) lgkmcnt(3)
	v_pk_mul_f32 v[46:47], v[46:47], v[110:111]
	v_pk_mul_f32 v[48:49], v[48:49], v[112:113]
	v_pk_fma_f32 v[188:189], v[188:189], s[98:99], v[46:47] op_sel_hi:[1,0,1]
	v_pk_fma_f32 v[190:191], v[190:191], s[98:99], v[48:49] op_sel_hi:[1,0,1]
	ds_read_b128 v[46:49], v116 offset:59168
	global_store_dwordx4 v114, v[188:191], s[16:17]
	s_add_u32 s16, s16, 0x8000
	s_addc_u32 s17, s17, 0
	s_waitcnt vmcnt(15) lgkmcnt(3)
	v_pk_mul_f32 v[50:51], v[50:51], v[110:111]
	v_pk_mul_f32 v[52:53], v[52:53], v[112:113]
	v_pk_fma_f32 v[192:193], v[192:193], s[98:99], v[50:51] op_sel_hi:[1,0,1]
	v_pk_fma_f32 v[194:195], v[194:195], s[98:99], v[52:53] op_sel_hi:[1,0,1]
	ds_read_b128 v[50:53], v116 offset:63392
	global_store_dwordx4 v114, v[192:195], s[16:17]
	s_add_u32 s16, s16, 0x8000
	s_addc_u32 s17, s17, 0
	s_waitcnt vmcnt(15) lgkmcnt(3)
	v_pk_mul_f32 v[38:39], v[38:39], v[110:111]
	v_pk_mul_f32 v[40:41], v[40:41], v[112:113]
	v_pk_fma_f32 v[196:197], v[196:197], s[98:99], v[38:39] op_sel_hi:[1,0,1]
	v_pk_fma_f32 v[198:199], v[198:199], s[98:99], v[40:41] op_sel_hi:[1,0,1]
	global_store_dwordx4 v114, v[196:199], s[16:17]
	s_add_u32 s16, s16, 0x8000
	s_addc_u32 s17, s17, 0
	s_waitcnt vmcnt(15) lgkmcnt(2)
	v_pk_mul_f32 v[42:43], v[42:43], v[110:111]
	v_pk_mul_f32 v[44:45], v[44:45], v[112:113]
	v_pk_fma_f32 v[200:201], v[200:201], s[98:99], v[42:43] op_sel_hi:[1,0,1]
	v_pk_fma_f32 v[202:203], v[202:203], s[98:99], v[44:45] op_sel_hi:[1,0,1]
	global_store_dwordx4 v114, v[200:203], s[16:17]
	s_add_u32 s16, s16, 0x8000
	s_addc_u32 s17, s17, 0
	s_waitcnt vmcnt(15) lgkmcnt(1)
	v_pk_mul_f32 v[46:47], v[46:47], v[110:111]
	v_pk_mul_f32 v[48:49], v[48:49], v[112:113]
	v_pk_fma_f32 v[204:205], v[204:205], s[98:99], v[46:47] op_sel_hi:[1,0,1]
	v_pk_fma_f32 v[206:207], v[206:207], s[98:99], v[48:49] op_sel_hi:[1,0,1]
	global_store_dwordx4 v114, v[204:207], s[16:17]
	s_add_u32 s16, s16, 0x8000
	s_addc_u32 s17, s17, 0
	s_waitcnt vmcnt(15) lgkmcnt(0)
	v_pk_mul_f32 v[50:51], v[50:51], v[110:111]
	v_pk_mul_f32 v[52:53], v[52:53], v[112:113]
	v_pk_fma_f32 v[208:209], v[208:209], s[98:99], v[50:51] op_sel_hi:[1,0,1]
	v_pk_fma_f32 v[210:211], v[210:211], s[98:99], v[52:53] op_sel_hi:[1,0,1]
	global_store_dwordx4 v114, v[208:211], s[16:17]
	s_add_i32 s30, s30, s22
	s_cmpk_lt_u32 s30, 0x60
	s_cbranch_scc1 .LBB0_634

.Lk_outl1_loop:
	s_barrier
	s_add_u32 m0, s31, 32768
	v_mfma_f32_16x16x32_bf16 v[94:97], v[108:111], v[140:143], v[94:97]
	ds_read_b128 v[18:21], v98 offset:32
	global_load_lds_dwordx4 v158, s[14:15] offset:0
	v_mfma_f32_16x16x32_bf16 v[90:93], v[108:111], v[144:147], v[90:93]
	ds_read_b128 v[38:41], v156 offset:32
	global_load_lds_dwordx4 v159, s[14:15] offset:1024
	v_mfma_f32_16x16x32_bf16 v[82:85], v[108:111], v[148:151], v[82:85]
	ds_read_b128 v[46:49], v156 offset:2080
	global_load_lds_dwordx4 v160, s[14:15] offset:2048
	v_mfma_f32_16x16x32_bf16 v[78:81], v[108:111], v[152:155], v[78:81]
	ds_read_b128 v[26:29], v98 offset:2080
	global_load_lds_dwordx4 v161, s[14:15] offset:3072
	s_add_u32 m0, s31, 49152
	v_mfma_f32_16x16x32_bf16 v[74:77], v[112:115], v[140:143], v[74:77]
	ds_read_b128 v[50:53], v156 offset:4128
	global_load_lds_dwordx4 v158, s[12:13] offset:0
	v_mfma_f32_16x16x32_bf16 v[70:73], v[112:115], v[144:147], v[70:73]
	ds_read_b128 v[54:57], v156 offset:6176
	global_load_lds_dwordx4 v159, s[12:13] offset:1024
	v_mfma_f32_16x16x32_bf16 v[66:69], v[112:115], v[148:151], v[66:69]
	ds_read_b128 v[30:33], v98 offset:4128
	global_load_lds_dwordx4 v160, s[12:13] offset:2048
	v_mfma_f32_16x16x32_bf16 v[62:65], v[112:115], v[152:155], v[62:65]
	ds_read_b128 v[34:37], v98 offset:6176
	global_load_lds_dwordx4 v161, s[12:13] offset:3072
	v_mfma_f32_16x16x32_bf16 v[58:61], v[116:119], v[140:143], v[58:61]
	v_mfma_f32_16x16x32_bf16 v[42:45], v[116:119], v[144:147], v[42:45]
	v_mfma_f32_16x16x32_bf16 v[22:25], v[116:119], v[148:151], v[22:25]
	v_mfma_f32_16x16x32_bf16 v[14:17], v[116:119], v[152:155], v[14:17]
	v_mfma_f32_16x16x32_bf16 v[10:13], v[136:139], v[140:143], v[10:13]
	v_mfma_f32_16x16x32_bf16 v[6:9], v[136:139], v[144:147], v[6:9]
	v_mfma_f32_16x16x32_bf16 v[2:5], v[136:139], v[148:151], v[2:5]
	v_mfma_f32_16x16x32_bf16 v[86:89], v[136:139], v[152:155], v[86:89]
	s_add_u32 s98, s98, 1
	s_and_b32 s98, s98, 15
	s_cmp_eq_u32 s98, 0
	s_cselect_b32 s99, 0x800, 0
	s_add_u32 s14, s14, 0x80
	s_addc_u32 s15, s15, 0
	s_sub_u32 s14, s14, s99
	s_subb_u32 s15, s15, 0
	s_add_u32 s12, s12, 0x80
	s_addc_u32 s13, s13, 0
	s_sub_u32 s12, s12, s99
	s_subb_u32 s13, s13, 0
	s_waitcnt lgkmcnt(0)
	v_mfma_f32_16x16x32_bf16 v[94:97], v[18:21], v[38:41], v[94:97]
	ds_read_b128 v[108:111], v107 offset:32
	v_mfma_f32_16x16x32_bf16 v[90:93], v[18:21], v[46:49], v[90:93]
	ds_read_b128 v[140:143], v157 offset:32
	v_mfma_f32_16x16x32_bf16 v[82:85], v[18:21], v[50:53], v[82:85]
	ds_read_b128 v[144:147], v157 offset:2080
	v_mfma_f32_16x16x32_bf16 v[78:81], v[18:21], v[54:57], v[78:81]
	ds_read_b128 v[112:115], v107 offset:2080
	v_mfma_f32_16x16x32_bf16 v[74:77], v[26:29], v[38:41], v[74:77]
	ds_read_b128 v[148:151], v157 offset:4128
	v_mfma_f32_16x16x32_bf16 v[70:73], v[26:29], v[46:49], v[70:73]
	ds_read_b128 v[152:155], v157 offset:6176
	v_mfma_f32_16x16x32_bf16 v[66:69], v[26:29], v[50:53], v[66:69]
	ds_read_b128 v[116:119], v107 offset:4128
	v_mfma_f32_16x16x32_bf16 v[62:65], v[26:29], v[54:57], v[62:65]
	ds_read_b128 v[136:139], v107 offset:6176
	v_mfma_f32_16x16x32_bf16 v[58:61], v[30:33], v[38:41], v[58:61]
	v_mfma_f32_16x16x32_bf16 v[42:45], v[30:33], v[46:49], v[42:45]
	v_mfma_f32_16x16x32_bf16 v[22:25], v[30:33], v[50:53], v[22:25]
	v_mfma_f32_16x16x32_bf16 v[14:17], v[30:33], v[54:57], v[14:17]
	v_mfma_f32_16x16x32_bf16 v[10:13], v[34:37], v[38:41], v[10:13]
	v_mfma_f32_16x16x32_bf16 v[6:9], v[34:37], v[46:49], v[6:9]
	v_mfma_f32_16x16x32_bf16 v[2:5], v[34:37], v[50:53], v[2:5]
	v_mfma_f32_16x16x32_bf16 v[86:89], v[34:37], v[54:57], v[86:89]
	s_waitcnt lgkmcnt(0)
	s_waitcnt vmcnt(0)
	s_barrier
	s_add_u32 m0, s31, 0
	v_mfma_f32_16x16x32_bf16 v[94:97], v[108:111], v[140:143], v[94:97]
	ds_read_b128 v[18:21], v98 offset:32800
	global_load_lds_dwordx4 v158, s[14:15] offset:0
	v_mfma_f32_16x16x32_bf16 v[90:93], v[108:111], v[144:147], v[90:93]
	ds_read_b128 v[38:41], v156 offset:32800
	global_load_lds_dwordx4 v159, s[14:15] offset:1024
	v_mfma_f32_16x16x32_bf16 v[82:85], v[108:111], v[148:151], v[82:85]
	ds_read_b128 v[46:49], v156 offset:34848
	global_load_lds_dwordx4 v160, s[14:15] offset:2048
	v_mfma_f32_16x16x32_bf16 v[78:81], v[108:111], v[152:155], v[78:81]
	ds_read_b128 v[26:29], v98 offset:34848
	global_load_lds_dwordx4 v161, s[14:15] offset:3072
	s_add_u32 m0, s31, 16384
	v_mfma_f32_16x16x32_bf16 v[74:77], v[112:115], v[140:143], v[74:77]
	ds_read_b128 v[50:53], v156 offset:36896
	global_load_lds_dwordx4 v158, s[12:13] offset:0
	v_mfma_f32_16x16x32_bf16 v[70:73], v[112:115], v[144:147], v[70:73]
	ds_read_b128 v[54:57], v156 offset:38944
	global_load_lds_dwordx4 v159, s[12:13] offset:1024
	v_mfma_f32_16x16x32_bf16 v[66:69], v[112:115], v[148:151], v[66:69]
	ds_read_b128 v[30:33], v98 offset:36896
	global_load_lds_dwordx4 v160, s[12:13] offset:2048
	v_mfma_f32_16x16x32_bf16 v[62:65], v[112:115], v[152:155], v[62:65]
	ds_read_b128 v[34:37], v98 offset:38944
	global_load_lds_dwordx4 v161, s[12:13] offset:3072
	v_mfma_f32_16x16x32_bf16 v[58:61], v[116:119], v[140:143], v[58:61]
	v_mfma_f32_16x16x32_bf16 v[42:45], v[116:119], v[144:147], v[42:45]
	v_mfma_f32_16x16x32_bf16 v[22:25], v[116:119], v[148:151], v[22:25]
	v_mfma_f32_16x16x32_bf16 v[14:17], v[116:119], v[152:155], v[14:17]
	v_mfma_f32_16x16x32_bf16 v[10:13], v[136:139], v[140:143], v[10:13]
	v_mfma_f32_16x16x32_bf16 v[6:9], v[136:139], v[144:147], v[6:9]
	v_mfma_f32_16x16x32_bf16 v[2:5], v[136:139], v[148:151], v[2:5]
	v_mfma_f32_16x16x32_bf16 v[86:89], v[136:139], v[152:155], v[86:89]
	s_add_u32 s98, s98, 1
	s_and_b32 s98, s98, 15
	s_cmp_eq_u32 s98, 0
	s_cselect_b32 s99, 0x800, 0
	s_add_u32 s14, s14, 0x80
	s_addc_u32 s15, s15, 0
	s_sub_u32 s14, s14, s99
	s_subb_u32 s15, s15, 0
	s_add_u32 s12, s12, 0x80
	s_addc_u32 s13, s13, 0
	s_sub_u32 s12, s12, s99
	s_subb_u32 s13, s13, 0
	s_waitcnt lgkmcnt(0)
	v_mfma_f32_16x16x32_bf16 v[94:97], v[18:21], v[38:41], v[94:97]
	ds_read_b128 v[108:111], v107 offset:32800
	v_mfma_f32_16x16x32_bf16 v[90:93], v[18:21], v[46:49], v[90:93]
	ds_read_b128 v[140:143], v157 offset:32800
	v_mfma_f32_16x16x32_bf16 v[82:85], v[18:21], v[50:53], v[82:85]
	ds_read_b128 v[144:147], v157 offset:34848
	v_mfma_f32_16x16x32_bf16 v[78:81], v[18:21], v[54:57], v[78:81]
	ds_read_b128 v[112:115], v107 offset:34848
	v_mfma_f32_16x16x32_bf16 v[74:77], v[26:29], v[38:41], v[74:77]
	ds_read_b128 v[148:151], v157 offset:36896
	v_mfma_f32_16x16x32_bf16 v[70:73], v[26:29], v[46:49], v[70:73]
	ds_read_b128 v[152:155], v157 offset:38944
	v_mfma_f32_16x16x32_bf16 v[66:69], v[26:29], v[50:53], v[66:69]
	ds_read_b128 v[116:119], v107 offset:36896
	v_mfma_f32_16x16x32_bf16 v[62:65], v[26:29], v[54:57], v[62:65]
	ds_read_b128 v[136:139], v107 offset:38944
	v_mfma_f32_16x16x32_bf16 v[58:61], v[30:33], v[38:41], v[58:61]
	v_mfma_f32_16x16x32_bf16 v[42:45], v[30:33], v[46:49], v[42:45]
	v_mfma_f32_16x16x32_bf16 v[22:25], v[30:33], v[50:53], v[22:25]
	v_mfma_f32_16x16x32_bf16 v[14:17], v[30:33], v[54:57], v[14:17]
	v_mfma_f32_16x16x32_bf16 v[10:13], v[34:37], v[38:41], v[10:13]
	v_mfma_f32_16x16x32_bf16 v[6:9], v[34:37], v[46:49], v[6:9]
	v_mfma_f32_16x16x32_bf16 v[2:5], v[34:37], v[50:53], v[2:5]
	v_mfma_f32_16x16x32_bf16 v[86:89], v[34:37], v[54:57], v[86:89]
	s_waitcnt lgkmcnt(0)
	s_waitcnt vmcnt(0)
	s_add_u32 s30, s30, 1
	s_cmp_lt_u32 s30, 7
	s_cbranch_scc1 .Lk_outl1_loop
	s_barrier
	s_add_u32 m0, s31, 32768
	v_mfma_f32_16x16x32_bf16 v[94:97], v[108:111], v[140:143], v[94:97]
	ds_read_b128 v[18:21], v98 offset:32
	global_load_lds_dwordx4 v158, s[14:15] offset:0
	v_mfma_f32_16x16x32_bf16 v[90:93], v[108:111], v[144:147], v[90:93]
	ds_read_b128 v[38:41], v156 offset:32
	global_load_lds_dwordx4 v159, s[14:15] offset:1024
	v_mfma_f32_16x16x32_bf16 v[82:85], v[108:111], v[148:151], v[82:85]
	ds_read_b128 v[46:49], v156 offset:2080
	global_load_lds_dwordx4 v160, s[14:15] offset:2048
	v_mfma_f32_16x16x32_bf16 v[78:81], v[108:111], v[152:155], v[78:81]
	ds_read_b128 v[26:29], v98 offset:2080
	global_load_lds_dwordx4 v161, s[14:15] offset:3072
	s_add_u32 m0, s31, 49152
	v_mfma_f32_16x16x32_bf16 v[74:77], v[112:115], v[140:143], v[74:77]
	ds_read_b128 v[50:53], v156 offset:4128
	global_load_lds_dwordx4 v158, s[12:13] offset:0
	v_mfma_f32_16x16x32_bf16 v[70:73], v[112:115], v[144:147], v[70:73]
	ds_read_b128 v[54:57], v156 offset:6176
	global_load_lds_dwordx4 v159, s[12:13] offset:1024
	v_mfma_f32_16x16x32_bf16 v[66:69], v[112:115], v[148:151], v[66:69]
	ds_read_b128 v[30:33], v98 offset:4128
	global_load_lds_dwordx4 v160, s[12:13] offset:2048
	v_mfma_f32_16x16x32_bf16 v[62:65], v[112:115], v[152:155], v[62:65]
	ds_read_b128 v[34:37], v98 offset:6176
	global_load_lds_dwordx4 v161, s[12:13] offset:3072
	v_mfma_f32_16x16x32_bf16 v[58:61], v[116:119], v[140:143], v[58:61]
	v_mfma_f32_16x16x32_bf16 v[42:45], v[116:119], v[144:147], v[42:45]
	v_mfma_f32_16x16x32_bf16 v[22:25], v[116:119], v[148:151], v[22:25]
	v_mfma_f32_16x16x32_bf16 v[14:17], v[116:119], v[152:155], v[14:17]
	v_mfma_f32_16x16x32_bf16 v[10:13], v[136:139], v[140:143], v[10:13]
	v_mfma_f32_16x16x32_bf16 v[6:9], v[136:139], v[144:147], v[6:9]
	v_mfma_f32_16x16x32_bf16 v[2:5], v[136:139], v[148:151], v[2:5]
	v_mfma_f32_16x16x32_bf16 v[86:89], v[136:139], v[152:155], v[86:89]
	s_add_u32 s98, s98, 1
	s_and_b32 s98, s98, 15
	s_cmp_eq_u32 s98, 0
	s_cselect_b32 s99, 0x800, 0
	s_add_u32 s14, s14, 0x80
	s_addc_u32 s15, s15, 0
	s_sub_u32 s14, s14, s99
	s_subb_u32 s15, s15, 0
	s_add_u32 s12, s12, 0x80
	s_addc_u32 s13, s13, 0
	s_sub_u32 s12, s12, s99
	s_subb_u32 s13, s13, 0
	s_waitcnt lgkmcnt(0)
	v_mfma_f32_16x16x32_bf16 v[94:97], v[18:21], v[38:41], v[94:97]
	ds_read_b128 v[108:111], v107 offset:32
	v_mfma_f32_16x16x32_bf16 v[90:93], v[18:21], v[46:49], v[90:93]
	ds_read_b128 v[140:143], v157 offset:32
	v_mfma_f32_16x16x32_bf16 v[82:85], v[18:21], v[50:53], v[82:85]
	ds_read_b128 v[144:147], v157 offset:2080
	v_mfma_f32_16x16x32_bf16 v[78:81], v[18:21], v[54:57], v[78:81]
	ds_read_b128 v[112:115], v107 offset:2080
	v_mfma_f32_16x16x32_bf16 v[74:77], v[26:29], v[38:41], v[74:77]
	ds_read_b128 v[148:151], v157 offset:4128
	v_mfma_f32_16x16x32_bf16 v[70:73], v[26:29], v[46:49], v[70:73]
	ds_read_b128 v[152:155], v157 offset:6176
	v_mfma_f32_16x16x32_bf16 v[66:69], v[26:29], v[50:53], v[66:69]
	ds_read_b128 v[116:119], v107 offset:4128
	v_mfma_f32_16x16x32_bf16 v[62:65], v[26:29], v[54:57], v[62:65]
	ds_read_b128 v[136:139], v107 offset:6176
	v_mfma_f32_16x16x32_bf16 v[58:61], v[30:33], v[38:41], v[58:61]
	v_mfma_f32_16x16x32_bf16 v[42:45], v[30:33], v[46:49], v[42:45]
	v_mfma_f32_16x16x32_bf16 v[22:25], v[30:33], v[50:53], v[22:25]
	v_mfma_f32_16x16x32_bf16 v[14:17], v[30:33], v[54:57], v[14:17]
	v_mfma_f32_16x16x32_bf16 v[10:13], v[34:37], v[38:41], v[10:13]
	v_mfma_f32_16x16x32_bf16 v[6:9], v[34:37], v[46:49], v[6:9]
	v_mfma_f32_16x16x32_bf16 v[2:5], v[34:37], v[50:53], v[2:5]
	v_mfma_f32_16x16x32_bf16 v[86:89], v[34:37], v[54:57], v[86:89]
	s_waitcnt lgkmcnt(0)
	s_waitcnt vmcnt(0)
	s_barrier
	v_mfma_f32_16x16x32_bf16 v[94:97], v[108:111], v[140:143], v[94:97]
	ds_read_b128 v[18:21], v98 offset:32800
	v_mfma_f32_16x16x32_bf16 v[90:93], v[108:111], v[144:147], v[90:93]
	ds_read_b128 v[38:41], v156 offset:32800
	v_mfma_f32_16x16x32_bf16 v[82:85], v[108:111], v[148:151], v[82:85]
	ds_read_b128 v[46:49], v156 offset:34848
	v_mfma_f32_16x16x32_bf16 v[78:81], v[108:111], v[152:155], v[78:81]
	ds_read_b128 v[26:29], v98 offset:34848
	v_mfma_f32_16x16x32_bf16 v[74:77], v[112:115], v[140:143], v[74:77]
	ds_read_b128 v[50:53], v156 offset:36896
	v_mfma_f32_16x16x32_bf16 v[70:73], v[112:115], v[144:147], v[70:73]
	ds_read_b128 v[54:57], v156 offset:38944
	v_mfma_f32_16x16x32_bf16 v[66:69], v[112:115], v[148:151], v[66:69]
	ds_read_b128 v[30:33], v98 offset:36896
	v_mfma_f32_16x16x32_bf16 v[62:65], v[112:115], v[152:155], v[62:65]
	ds_read_b128 v[34:37], v98 offset:38944
	v_mfma_f32_16x16x32_bf16 v[58:61], v[116:119], v[140:143], v[58:61]
	v_mfma_f32_16x16x32_bf16 v[42:45], v[116:119], v[144:147], v[42:45]
	v_mfma_f32_16x16x32_bf16 v[22:25], v[116:119], v[148:151], v[22:25]
	v_mfma_f32_16x16x32_bf16 v[14:17], v[116:119], v[152:155], v[14:17]
	v_mfma_f32_16x16x32_bf16 v[10:13], v[136:139], v[140:143], v[10:13]
	v_mfma_f32_16x16x32_bf16 v[6:9], v[136:139], v[144:147], v[6:9]
	v_mfma_f32_16x16x32_bf16 v[2:5], v[136:139], v[148:151], v[2:5]
	v_mfma_f32_16x16x32_bf16 v[86:89], v[136:139], v[152:155], v[86:89]
	s_waitcnt lgkmcnt(0)
	v_mfma_f32_16x16x32_bf16 v[94:97], v[18:21], v[38:41], v[94:97]
	ds_read_b128 v[108:111], v107 offset:32800
	v_mfma_f32_16x16x32_bf16 v[90:93], v[18:21], v[46:49], v[90:93]
	ds_read_b128 v[140:143], v157 offset:32800
	v_mfma_f32_16x16x32_bf16 v[82:85], v[18:21], v[50:53], v[82:85]
	ds_read_b128 v[144:147], v157 offset:34848
	v_mfma_f32_16x16x32_bf16 v[78:81], v[18:21], v[54:57], v[78:81]
	ds_read_b128 v[112:115], v107 offset:34848
	v_mfma_f32_16x16x32_bf16 v[74:77], v[26:29], v[38:41], v[74:77]
	ds_read_b128 v[148:151], v157 offset:36896
	v_mfma_f32_16x16x32_bf16 v[70:73], v[26:29], v[46:49], v[70:73]
	ds_read_b128 v[152:155], v157 offset:38944
	v_mfma_f32_16x16x32_bf16 v[66:69], v[26:29], v[50:53], v[66:69]
	ds_read_b128 v[116:119], v107 offset:36896
	v_mfma_f32_16x16x32_bf16 v[62:65], v[26:29], v[54:57], v[62:65]
	ds_read_b128 v[136:139], v107 offset:38944
	v_mfma_f32_16x16x32_bf16 v[58:61], v[30:33], v[38:41], v[58:61]
	v_mfma_f32_16x16x32_bf16 v[42:45], v[30:33], v[46:49], v[42:45]
	v_mfma_f32_16x16x32_bf16 v[22:25], v[30:33], v[50:53], v[22:25]
	v_mfma_f32_16x16x32_bf16 v[14:17], v[30:33], v[54:57], v[14:17]
	v_mfma_f32_16x16x32_bf16 v[10:13], v[34:37], v[38:41], v[10:13]
	v_mfma_f32_16x16x32_bf16 v[6:9], v[34:37], v[46:49], v[6:9]
	v_mfma_f32_16x16x32_bf16 v[2:5], v[34:37], v[50:53], v[2:5]
	v_mfma_f32_16x16x32_bf16 v[86:89], v[34:37], v[54:57], v[86:89]
	s_waitcnt lgkmcnt(0)
	v_mfma_f32_16x16x32_bf16 v[94:97], v[108:111], v[140:143], v[94:97]
	v_mfma_f32_16x16x32_bf16 v[90:93], v[108:111], v[144:147], v[90:93]
	v_mfma_f32_16x16x32_bf16 v[82:85], v[108:111], v[148:151], v[82:85]
	v_mfma_f32_16x16x32_bf16 v[78:81], v[108:111], v[152:155], v[78:81]
	v_mfma_f32_16x16x32_bf16 v[74:77], v[112:115], v[140:143], v[74:77]
	v_mfma_f32_16x16x32_bf16 v[70:73], v[112:115], v[144:147], v[70:73]
	v_mfma_f32_16x16x32_bf16 v[66:69], v[112:115], v[148:151], v[66:69]
	v_mfma_f32_16x16x32_bf16 v[62:65], v[112:115], v[152:155], v[62:65]
	v_mfma_f32_16x16x32_bf16 v[58:61], v[116:119], v[140:143], v[58:61]
	v_mfma_f32_16x16x32_bf16 v[42:45], v[116:119], v[144:147], v[42:45]
	v_mfma_f32_16x16x32_bf16 v[22:25], v[116:119], v[148:151], v[22:25]
	v_mfma_f32_16x16x32_bf16 v[14:17], v[116:119], v[152:155], v[14:17]
	v_mfma_f32_16x16x32_bf16 v[10:13], v[136:139], v[140:143], v[10:13]
	v_mfma_f32_16x16x32_bf16 v[6:9], v[136:139], v[144:147], v[6:9]
	v_mfma_f32_16x16x32_bf16 v[2:5], v[136:139], v[148:151], v[2:5]
	v_mfma_f32_16x16x32_bf16 v[86:89], v[136:139], v[152:155], v[86:89]
	s_mul_i32 s12, s29, 12
	s_sub_u32 s12, s28, s12
	v_readlane_b32 s13, v255, 16
	s_and_b32 s13, s13, 7
	s_lshl_b32 s12, s12, 3
	s_or_b32 s12, s12, s13
	s_lshl_b32 s100, s12, 7
	s_lshl_b32 s101, s29, 9
	v_lshrrev_b32_e32 v112, 5, v0
	v_and_b32_e32 v112, 7, v112
	v_and_b32_e32 v113, 31, v0
	v_lshlrev_b32_e32 v113, 4, v113
	v_lshl_or_b32 v112, v112, 12, v113
	s_sub_u32 s12, s100, 0x2000
	s_lshr_b32 s12, s12, 10
	s_add_u32 s12, s12, 1
	s_cmp_lt_u32 s100, 0x2000
	s_cselect_b32 s12, 0, s12
	s_mul_i32 s12, s12, 0x6000
	s_add_u32 s12, s12, s101
	s_add_u32 s14, s42, s12
	s_addc_u32 s15, s43, 0
	s_add_u32 s14, s14, 0x6ec4000
	s_addc_u32 s15, s15, 0
	global_load_dwordx4 v[108:111], v113, s[14:15]
	s_lshl_b32 s12, s100, 12
	s_add_u32 s12, s12, s101
	s_add_u32 s14, s42, s12
	s_addc_u32 s15, s43, 0
	s_add_u32 s14, s14, 0x6f24000
	s_addc_u32 s15, s15, 0
	global_load_dwordx4 v[136:139], v112, s[14:15] nt
	s_add_u32 s14, s14, 0x8000
	s_addc_u32 s15, s15, 0
	global_load_dwordx4 v[140:143], v112, s[14:15] nt
	s_add_u32 s14, s14, 0x8000
	s_addc_u32 s15, s15, 0
	global_load_dwordx4 v[144:147], v112, s[14:15] nt
	s_add_u32 s14, s14, 0x8000
	s_addc_u32 s15, s15, 0
	global_load_dwordx4 v[148:151], v112, s[14:15] nt
	s_add_u32 s14, s14, 0x8000
	s_addc_u32 s15, s15, 0
	global_load_dwordx4 v[152:155], v112, s[14:15] nt
	s_add_u32 s14, s14, 0x8000
	s_addc_u32 s15, s15, 0
	global_load_dwordx4 v[156:159], v112, s[14:15] nt
	s_add_u32 s14, s14, 0x8000
	s_addc_u32 s15, s15, 0
	global_load_dwordx4 v[160:163], v112, s[14:15] nt
	s_add_u32 s14, s14, 0x8000
	s_addc_u32 s15, s15, 0
	global_load_dwordx4 v[164:167], v112, s[14:15] nt
	s_add_u32 s14, s14, 0x8000
	s_addc_u32 s15, s15, 0
	global_load_dwordx4 v[168:171], v112, s[14:15] nt
	s_add_u32 s14, s14, 0x8000
	s_addc_u32 s15, s15, 0
	global_load_dwordx4 v[172:175], v112, s[14:15] nt
	s_add_u32 s14, s14, 0x8000
	s_addc_u32 s15, s15, 0
	global_load_dwordx4 v[176:179], v112, s[14:15] nt
	s_add_u32 s14, s14, 0x8000
	s_addc_u32 s15, s15, 0
	global_load_dwordx4 v[180:183], v112, s[14:15] nt
	s_add_u32 s14, s14, 0x8000
	s_addc_u32 s15, s15, 0
	global_load_dwordx4 v[184:187], v112, s[14:15] nt
	s_add_u32 s14, s14, 0x8000
	s_addc_u32 s15, s15, 0
	global_load_dwordx4 v[188:191], v112, s[14:15] nt
	s_add_u32 s14, s14, 0x8000
	s_addc_u32 s15, s15, 0
	global_load_dwordx4 v[192:195], v112, s[14:15] nt
	s_add_u32 s14, s14, 0x8000
	s_addc_u32 s15, s15, 0
	global_load_dwordx4 v[196:199], v112, s[14:15] nt
	v_add_u32_e32 v18, 0x400, v123
	s_barrier
	ds_write2_b32 v123, v94, v90 offset1:16
	ds_write2_b32 v123, v95, v91 offset0:132 offset1:148
	ds_write2_b32 v18, v96, v92 offset0:8 offset1:24
	ds_write2_b32 v18, v97, v93 offset0:140 offset1:156
	ds_write2_b32 v123, v82, v78 offset0:32 offset1:48
	ds_write2_b32 v123, v83, v79 offset0:164 offset1:180
	ds_write2_b32 v18, v84, v80 offset0:40 offset1:56
	ds_write2_b32 v18, v85, v81 offset0:172 offset1:188
	v_add_u32_e32 v18, 0x2000, v123
	v_add_u32_e32 v19, 0x2400, v123
	ds_write2_b32 v18, v74, v70 offset0:64 offset1:80
	ds_write2_b32 v18, v75, v71 offset0:196 offset1:212
	ds_write2_b32 v19, v76, v72 offset0:72 offset1:88
	ds_write2_b32 v19, v77, v73 offset0:204 offset1:220
	ds_write2_b32 v18, v66, v62 offset0:96 offset1:112
	ds_write2_b32 v18, v67, v63 offset0:228 offset1:244
	ds_write2_b32 v19, v68, v64 offset0:104 offset1:120
	ds_write2_b32 v19, v69, v65 offset0:236 offset1:252
	v_add_u32_e32 v18, 0x4000, v123
	v_add_u32_e32 v19, 0x4400, v123
	v_add_u32_e32 v20, 0x4800, v123
	ds_write2_b32 v18, v58, v42 offset0:128 offset1:144
	ds_write2_b32 v19, v59, v43 offset0:4 offset1:20
	ds_write2_b32 v19, v60, v44 offset0:136 offset1:152
	ds_write2_b32 v20, v61, v45 offset0:12 offset1:28
	ds_write2_b32 v18, v22, v14 offset0:160 offset1:176
	ds_write2_b32 v19, v23, v15 offset0:36 offset1:52
	ds_write2_b32 v19, v24, v16 offset0:168 offset1:184
	ds_write2_b32 v20, v25, v17 offset0:44 offset1:60
	v_add_u32_e32 v14, 0x6000, v123
	ds_write2_b32 v14, v10, v6 offset0:192 offset1:208
	v_add_u32_e32 v6, 0x6400, v123
	ds_write2_b32 v6, v11, v7 offset0:68 offset1:84
	ds_write2_b32 v6, v12, v8 offset0:200 offset1:216
	v_add_u32_e32 v7, 0x6800, v123
	s_lshl_b32 s2, s29, 9
	ds_write2_b32 v7, v13, v9 offset0:76 offset1:92
	ds_write2_b32 v14, v2, v86 offset0:224 offset1:240
	ds_write2_b32 v6, v3, v87 offset0:100 offset1:116
	ds_write2_b32 v6, v4, v88 offset0:232 offset1:248
	ds_write2_b32 v7, v5, v89 offset0:108 offset1:124
	v_lshl_add_u64 v[2:3], v[100:101], 0, s[2:3]
	v_lshl_add_u64 v[4:5], v[102:103], 0, s[2:3]
	s_lshl_b32 s2, s28, 10
	s_mul_hi_u32 s12, s28, 0x15555556
	s_lshl_b32 s13, s29, 7
	v_or_b32_e32 v6, s2, v125
	s_mulk_i32 s12, 0x3000
	v_or_b32_e32 v7, s2, v127
	v_or_b32_e32 v8, s2, v129
	v_or_b32_e32 v9, s2, v133
	v_subrev_u32_e32 v6, s12, v6
	v_subrev_u32_e32 v7, s12, v7
	v_subrev_u32_e32 v8, s12, v8
	v_subrev_u32_e32 v9, s12, v9
	s_mov_b32 s12, 0
	s_lshl_b32 s2, s13, 2
	v_mov_b32_e32 v10, v132
	v_mov_b32_e32 v11, v128
	v_mov_b32_e32 v12, v126
	v_mov_b32_e32 v13, v124
	s_waitcnt lgkmcnt(0)
	s_barrier
	s_mov_b32 s98, 0x3fb504f3
	v_lshrrev_b32_e32 v114, 5, v0
	v_and_b32_e32 v114, 7, v114
	v_mul_u32_u24_e32 v114, 0x210, v114
	v_and_b32_e32 v26, 31, v0
	v_lshl_add_u32 v114, v26, 4, v114
	s_lshl_b32 s12, s100, 12
	s_add_u32 s12, s12, s101
	s_add_u32 s14, s42, s12
	s_addc_u32 s15, s43, 0
	s_add_u32 s14, s14, 0xfb24000
	s_addc_u32 s15, s15, 0
	ds_read_b128 v[26:29], v114 offset:32
	ds_read_b128 v[30:33], v114 offset:4256
	ds_read_b128 v[34:37], v114 offset:8480
	ds_read_b128 v[38:41], v114 offset:12704
	s_waitcnt vmcnt(15) lgkmcnt(3)
	v_pk_mul_f32 v[26:27], v[26:27], v[108:109]
	v_pk_mul_f32 v[28:29], v[28:29], v[110:111]
	v_pk_fma_f32 v[136:137], v[136:137], s[98:99], v[26:27] op_sel_hi:[1,0,1]
	v_pk_fma_f32 v[138:139], v[138:139], s[98:99], v[28:29] op_sel_hi:[1,0,1]
	ds_read_b128 v[26:29], v114 offset:16928
	global_store_dwordx4 v112, v[136:139], s[14:15]
	s_add_u32 s14, s14, 0x8000
	s_addc_u32 s15, s15, 0
	s_waitcnt vmcnt(15) lgkmcnt(3)
	v_pk_mul_f32 v[30:31], v[30:31], v[108:109]
	v_pk_mul_f32 v[32:33], v[32:33], v[110:111]
	v_pk_fma_f32 v[140:141], v[140:141], s[98:99], v[30:31] op_sel_hi:[1,0,1]
	v_pk_fma_f32 v[142:143], v[142:143], s[98:99], v[32:33] op_sel_hi:[1,0,1]
	ds_read_b128 v[30:33], v114 offset:21152
	global_store_dwordx4 v112, v[140:143], s[14:15]
	s_add_u32 s14, s14, 0x8000
	s_addc_u32 s15, s15, 0
	s_waitcnt vmcnt(15) lgkmcnt(3)
	v_pk_mul_f32 v[34:35], v[34:35], v[108:109]
	v_pk_mul_f32 v[36:37], v[36:37], v[110:111]
	v_pk_fma_f32 v[144:145], v[144:145], s[98:99], v[34:35] op_sel_hi:[1,0,1]
	v_pk_fma_f32 v[146:147], v[146:147], s[98:99], v[36:37] op_sel_hi:[1,0,1]
	ds_read_b128 v[34:37], v114 offset:25376
	global_store_dwordx4 v112, v[144:147], s[14:15]
	s_add_u32 s14, s14, 0x8000
	s_addc_u32 s15, s15, 0
	s_waitcnt vmcnt(15) lgkmcnt(3)
	v_pk_mul_f32 v[38:39], v[38:39], v[108:109]
	v_pk_mul_f32 v[40:41], v[40:41], v[110:111]
	v_pk_fma_f32 v[148:149], v[148:149], s[98:99], v[38:39] op_sel_hi:[1,0,1]
	v_pk_fma_f32 v[150:151], v[150:151], s[98:99], v[40:41] op_sel_hi:[1,0,1]
	ds_read_b128 v[38:41], v114 offset:29600
	global_store_dwordx4 v112, v[148:151], s[14:15]
	s_add_u32 s14, s14, 0x8000
	s_addc_u32 s15, s15, 0
	s_waitcnt vmcnt(15) lgkmcnt(3)
	v_pk_mul_f32 v[26:27], v[26:27], v[108:109]
	v_pk_mul_f32 v[28:29], v[28:29], v[110:111]
	v_pk_fma_f32 v[152:153], v[152:153], s[98:99], v[26:27] op_sel_hi:[1,0,1]
	v_pk_fma_f32 v[154:155], v[154:155], s[98:99], v[28:29] op_sel_hi:[1,0,1]
	ds_read_b128 v[26:29], v114 offset:33824
	global_store_dwordx4 v112, v[152:155], s[14:15]
	s_add_u32 s14, s14, 0x8000
	s_addc_u32 s15, s15, 0
	s_waitcnt vmcnt(15) lgkmcnt(3)
	v_pk_mul_f32 v[30:31], v[30:31], v[108:109]
	v_pk_mul_f32 v[32:33], v[32:33], v[110:111]
	v_pk_fma_f32 v[156:157], v[156:157], s[98:99], v[30:31] op_sel_hi:[1,0,1]
	v_pk_fma_f32 v[158:159], v[158:159], s[98:99], v[32:33] op_sel_hi:[1,0,1]
	ds_read_b128 v[30:33], v114 offset:38048
	global_store_dwordx4 v112, v[156:159], s[14:15]
	s_add_u32 s14, s14, 0x8000
	s_addc_u32 s15, s15, 0
	s_waitcnt vmcnt(15) lgkmcnt(3)
	v_pk_mul_f32 v[34:35], v[34:35], v[108:109]
	v_pk_mul_f32 v[36:37], v[36:37], v[110:111]
	v_pk_fma_f32 v[160:161], v[160:161], s[98:99], v[34:35] op_sel_hi:[1,0,1]
	v_pk_fma_f32 v[162:163], v[162:163], s[98:99], v[36:37] op_sel_hi:[1,0,1]
	ds_read_b128 v[34:37], v114 offset:42272
	global_store_dwordx4 v112, v[160:163], s[14:15]
	s_add_u32 s14, s14, 0x8000
	s_addc_u32 s15, s15, 0
	s_waitcnt vmcnt(15) lgkmcnt(3)
	v_pk_mul_f32 v[38:39], v[38:39], v[108:109]
	v_pk_mul_f32 v[40:41], v[40:41], v[110:111]
	v_pk_fma_f32 v[164:165], v[164:165], s[98:99], v[38:39] op_sel_hi:[1,0,1]
	v_pk_fma_f32 v[166:167], v[166:167], s[98:99], v[40:41] op_sel_hi:[1,0,1]
	ds_read_b128 v[38:41], v114 offset:46496
	global_store_dwordx4 v112, v[164:167], s[14:15]
	s_add_u32 s14, s14, 0x8000
	s_addc_u32 s15, s15, 0
	s_waitcnt vmcnt(15) lgkmcnt(3)
	v_pk_mul_f32 v[26:27], v[26:27], v[108:109]
	v_pk_mul_f32 v[28:29], v[28:29], v[110:111]
	v_pk_fma_f32 v[168:169], v[168:169], s[98:99], v[26:27] op_sel_hi:[1,0,1]
	v_pk_fma_f32 v[170:171], v[170:171], s[98:99], v[28:29] op_sel_hi:[1,0,1]
	ds_read_b128 v[26:29], v114 offset:50720
	global_store_dwordx4 v112, v[168:171], s[14:15]
	s_add_u32 s14, s14, 0x8000
	s_addc_u32 s15, s15, 0
	s_waitcnt vmcnt(15) lgkmcnt(3)
	v_pk_mul_f32 v[30:31], v[30:31], v[108:109]
	v_pk_mul_f32 v[32:33], v[32:33], v[110:111]
	v_pk_fma_f32 v[172:173], v[172:173], s[98:99], v[30:31] op_sel_hi:[1,0,1]
	v_pk_fma_f32 v[174:175], v[174:175], s[98:99], v[32:33] op_sel_hi:[1,0,1]
	ds_read_b128 v[30:33], v114 offset:54944
	global_store_dwordx4 v112, v[172:175], s[14:15]
	s_add_u32 s14, s14, 0x8000
	s_addc_u32 s15, s15, 0
	s_waitcnt vmcnt(15) lgkmcnt(3)
	v_pk_mul_f32 v[34:35], v[34:35], v[108:109]
	v_pk_mul_f32 v[36:37], v[36:37], v[110:111]
	v_pk_fma_f32 v[176:177], v[176:177], s[98:99], v[34:35] op_sel_hi:[1,0,1]
	v_pk_fma_f32 v[178:179], v[178:179], s[98:99], v[36:37] op_sel_hi:[1,0,1]
	ds_read_b128 v[34:37], v114 offset:59168
	global_store_dwordx4 v112, v[176:179], s[14:15]
	s_add_u32 s14, s14, 0x8000
	s_addc_u32 s15, s15, 0
	s_waitcnt vmcnt(15) lgkmcnt(3)
	v_pk_mul_f32 v[38:39], v[38:39], v[108:109]
	v_pk_mul_f32 v[40:41], v[40:41], v[110:111]
	v_pk_fma_f32 v[180:181], v[180:181], s[98:99], v[38:39] op_sel_hi:[1,0,1]
	v_pk_fma_f32 v[182:183], v[182:183], s[98:99], v[40:41] op_sel_hi:[1,0,1]
	ds_read_b128 v[38:41], v114 offset:63392
	global_store_dwordx4 v112, v[180:183], s[14:15]
	s_add_u32 s14, s14, 0x8000
	s_addc_u32 s15, s15, 0
	s_waitcnt vmcnt(15) lgkmcnt(3)
	v_pk_mul_f32 v[26:27], v[26:27], v[108:109]
	v_pk_mul_f32 v[28:29], v[28:29], v[110:111]
	v_pk_fma_f32 v[184:185], v[184:185], s[98:99], v[26:27] op_sel_hi:[1,0,1]
	v_pk_fma_f32 v[186:187], v[186:187], s[98:99], v[28:29] op_sel_hi:[1,0,1]
	global_store_dwordx4 v112, v[184:187], s[14:15]
	s_add_u32 s14, s14, 0x8000
	s_addc_u32 s15, s15, 0
	s_waitcnt vmcnt(15) lgkmcnt(2)
	v_pk_mul_f32 v[30:31], v[30:31], v[108:109]
	v_pk_mul_f32 v[32:33], v[32:33], v[110:111]
	v_pk_fma_f32 v[188:189], v[188:189], s[98:99], v[30:31] op_sel_hi:[1,0,1]
	v_pk_fma_f32 v[190:191], v[190:191], s[98:99], v[32:33] op_sel_hi:[1,0,1]
	global_store_dwordx4 v112, v[188:191], s[14:15]
	s_add_u32 s14, s14, 0x8000
	s_addc_u32 s15, s15, 0
	s_waitcnt vmcnt(15) lgkmcnt(1)
	v_pk_mul_f32 v[34:35], v[34:35], v[108:109]
	v_pk_mul_f32 v[36:37], v[36:37], v[110:111]
	v_pk_fma_f32 v[192:193], v[192:193], s[98:99], v[34:35] op_sel_hi:[1,0,1]
	v_pk_fma_f32 v[194:195], v[194:195], s[98:99], v[36:37] op_sel_hi:[1,0,1]
	global_store_dwordx4 v112, v[192:195], s[14:15]
	s_add_u32 s14, s14, 0x8000
	s_addc_u32 s15, s15, 0
	s_waitcnt vmcnt(15) lgkmcnt(0)
	v_pk_mul_f32 v[38:39], v[38:39], v[108:109]
	v_pk_mul_f32 v[40:41], v[40:41], v[110:111]
	v_pk_fma_f32 v[196:197], v[196:197], s[98:99], v[38:39] op_sel_hi:[1,0,1]
	v_pk_fma_f32 v[198:199], v[198:199], s[98:99], v[40:41] op_sel_hi:[1,0,1]
	global_store_dwordx4 v112, v[196:199], s[14:15]
	s_add_i32 s11, s11, s20
	s_cmpk_lt_u32 s11, 0x60
	s_cbranch_scc1 .LBB0_1372
